# v31 plus longer s_sleep in the cooperative grid.sync spin loop
# speedup vs baseline: 1.0044x; 1.0044x over previous
; __global__ void __launch_bounds__(256, 2) fwd_megakernel(Params P) {
;     ...
;   grid.sync();
.LBB0_101:
	s_sleep 16
	global_load_dword v5, v0, s[4:5] offset:32 sc1
	s_waitcnt vmcnt(0)
	v_and_b32_e32 v5, 0xffff0000, v5
	v_cmp_ne_u32_e32 vcc, v5, v1
	s_or_b64 s[8:9], vcc, s[8:9]
	s_andn2_b64 exec, exec, s[8:9]
	s_cbranch_execnz .LBB0_101
